# gather unit new-key and stats butterflies and HGRN rms-norm shuffles converted from ds_bpermute hops to DPP adds plus readlanes (same pairing and association)
# speedup vs baseline: 1.0206x; 1.0020x over previous
.LBB0_2332:
	s_bfe_u32 s23, s54, 0x50003
	v_mbcnt_lo_u32_b32 v241, -1, 0
	v_mbcnt_hi_u32_b32 v241, -1, v241
	v_lshlrev_b32_e32 v241, 2, v241
	v_lshl_or_b32 v241, s23, 8, v241
	global_load_dword v240, v241, s[28:29]
	s_lshl_b32 s59, s23, 3
	s_and_b32 s22, s54, 7
	s_or_b32 s20, s59, 0x4000
	v_readfirstlane_b32 s55, v149
	s_or_b32 s58, s20, s22
	s_add_i32 s20, s55, s20
	s_ashr_i32 s21, s20, 31
	s_lshl_b32 s30, s58, 11
	s_lshl_b64 s[20:21], s[20:21], 7
	v_lshl_add_u64 v[4:5], v[140:141], 0, s[30:31]
	v_lshl_add_u64 v[12:13], v[142:143], 0, s[20:21]
	global_load_dwordx4 v[0:3], v[4:5], off
	s_nop 0
	global_load_dwordx4 v[4:7], v[4:5], off offset:16
	s_nop 0
	global_load_dwordx4 v[8:11], v[12:13], off
	s_nop 0
	global_load_dwordx4 v[12:15], v[12:13], off offset:16
	s_lshl_b32 s30, s58, 6
	v_lshl_add_u64 v[16:17], v[144:145], 0, s[30:31]
	global_load_dword v16, v[16:17], off
	s_and_b32 s20, s54, 0xff
	s_mul_i32 s30, s20, 0x8100
	v_lshl_add_u64 v[244:245], v[146:147], 0, s[30:31]
	global_load_dword v222, v[244:245], off
	global_load_dword v223, v[244:245], off offset:2048
	v_add_co_u32_e32 v246, vcc, 0x1000, v244
	s_nop 1
	v_addc_co_u32_e32 v247, vcc, 0, v245, vcc
	global_load_dword v224, v[246:247], off
	global_load_dword v225, v[246:247], off offset:2048
	v_add_co_u32_e32 v246, vcc, 0x2000, v244
	s_nop 1
	v_addc_co_u32_e32 v247, vcc, 0, v245, vcc
	global_load_dword v226, v[246:247], off
	global_load_dword v227, v[246:247], off offset:2048
	v_add_co_u32_e32 v246, vcc, 0x3000, v244
	s_nop 1
	v_addc_co_u32_e32 v247, vcc, 0, v245, vcc
	global_load_dword v228, v[246:247], off
	global_load_dword v229, v[246:247], off offset:2048
	v_add_co_u32_e32 v246, vcc, 0x4000, v244
	s_nop 1
	v_addc_co_u32_e32 v247, vcc, 0, v245, vcc
	global_load_dword v230, v[246:247], off
	global_load_dword v231, v[246:247], off offset:2048
	v_add_co_u32_e32 v246, vcc, 0x5000, v244
	s_nop 1
	v_addc_co_u32_e32 v247, vcc, 0, v245, vcc
	global_load_dword v232, v[246:247], off
	global_load_dword v233, v[246:247], off offset:2048
	v_add_co_u32_e32 v246, vcc, 0x6000, v244
	s_nop 1
	v_addc_co_u32_e32 v247, vcc, 0, v245, vcc
	global_load_dword v234, v[246:247], off
	global_load_dword v235, v[246:247], off offset:2048
	v_add_co_u32_e32 v246, vcc, 0x7000, v244
	s_nop 1
	v_addc_co_u32_e32 v247, vcc, 0, v245, vcc
	global_load_dword v236, v[246:247], off
	global_load_dword v237, v[246:247], off offset:2048
	s_waitcnt vmcnt(20)
	v_lshlrev_b32_e32 v17, 16, v0
	s_waitcnt vmcnt(18)
	v_lshlrev_b32_e32 v25, 16, v8
	v_and_b32_e32 v0, 0xffff0000, v0
	v_and_b32_e32 v8, 0xffff0000, v8
	v_fma_f32 v17, v17, v25, 0
	v_lshlrev_b32_e32 v18, 16, v1
	v_lshlrev_b32_e32 v26, 16, v9
	v_fmac_f32_e32 v17, v0, v8
	v_and_b32_e32 v1, 0xffff0000, v1
	v_and_b32_e32 v9, 0xffff0000, v9
	v_fmac_f32_e32 v17, v18, v26
	v_lshlrev_b32_e32 v19, 16, v2
	v_lshlrev_b32_e32 v27, 16, v10
	v_fmac_f32_e32 v17, v1, v9
	v_and_b32_e32 v2, 0xffff0000, v2
	v_and_b32_e32 v10, 0xffff0000, v10
	v_fmac_f32_e32 v17, v19, v27
	v_lshlrev_b32_e32 v20, 16, v3
	v_lshlrev_b32_e32 v28, 16, v11
	v_fmac_f32_e32 v17, v2, v10
	v_and_b32_e32 v3, 0xffff0000, v3
	v_and_b32_e32 v11, 0xffff0000, v11
	v_fmac_f32_e32 v17, v20, v28
	v_lshlrev_b32_e32 v21, 16, v4
	s_waitcnt vmcnt(17)
	v_lshlrev_b32_e32 v29, 16, v12
	v_fmac_f32_e32 v17, v3, v11
	v_and_b32_e32 v4, 0xffff0000, v4
	v_and_b32_e32 v12, 0xffff0000, v12
	v_fmac_f32_e32 v17, v21, v29
	v_lshlrev_b32_e32 v22, 16, v5
	v_lshlrev_b32_e32 v30, 16, v13
	v_fmac_f32_e32 v17, v4, v12
	v_and_b32_e32 v5, 0xffff0000, v5
	v_and_b32_e32 v13, 0xffff0000, v13
	v_fmac_f32_e32 v17, v22, v30
	v_lshlrev_b32_e32 v23, 16, v6
	v_lshlrev_b32_e32 v31, 16, v14
	v_fmac_f32_e32 v17, v5, v13
	v_and_b32_e32 v6, 0xffff0000, v6
	v_and_b32_e32 v14, 0xffff0000, v14
	v_fmac_f32_e32 v17, v23, v31
	v_lshlrev_b32_e32 v24, 16, v7
	v_lshlrev_b32_e32 v32, 16, v15
	v_fmac_f32_e32 v17, v6, v14
	v_and_b32_e32 v7, 0xffff0000, v7
	v_fmac_f32_e32 v17, v24, v32
	v_and_b32_e32 v0, 0xffff0000, v15
	v_fmac_f32_e32 v17, v7, v0
	s_nop 1
	v_add_f32_dpp v0, v17, v17 quad_perm:[1,0,3,2] row_mask:0xf bank_mask:0xf bound_ctrl:1
	s_nop 1
	v_add_f32_dpp v0, v0, v0 quad_perm:[2,3,0,1] row_mask:0xf bank_mask:0xf bound_ctrl:1
	v_max_f32_e32 v0, 0, v0
	s_waitcnt vmcnt(16)
	v_mul_f32_e32 v1, v16, v0
	s_nop 1
	v_mov_b32_dpp v1, v1 row_half_mirror row_mask:0xf bank_mask:0xf bound_ctrl:1
	v_fmac_f32_e32 v1, v16, v0
	s_nop 1
	v_add_f32_dpp v0, v1, v1 row_ror:8 row_mask:0xf bank_mask:0xf
	s_nop 0
	v_readlane_b32 s98, v0, 16
	v_readlane_b32 s99, v0, 32
	v_readlane_b32 s100, v0, 48
	s_nop 1
	v_add_f32_e32 v0, s98, v0
	v_mov_b32_e32 v1, s99
	v_add_f32_e32 v1, s100, v1
	s_and_saveexec_b64 s[20:21], s[0:1]
	s_cbranch_execz .LBB0_2334
	s_cmp_le_i32 s55, s22
	s_cselect_b64 vcc, -1, 0
	s_lshl_b32 s30, s55, 2
	s_waitcnt lgkmcnt(0)
	v_add_f32_e32 v0, v0, v1
	s_add_i32 s30, s30, 0
	v_cndmask_b32_e32 v0, v217, v0, vcc
	v_mov_b32_e32 v1, s30
	ds_write_b32 v1, v0 offset:256
.LBB0_2334:
	s_or_b64 exec, exec, s[20:21]
	s_waitcnt vmcnt(0) lgkmcnt(0)
	v_mov_b32_e32 v19, v222
	v_mov_b32_e32 v18, v223
	v_mov_b32_e32 v17, v224
	v_mov_b32_e32 v16, v225
	v_mov_b32_e32 v15, v226
	v_mov_b32_e32 v14, v227
	v_mov_b32_e32 v13, v228
	v_mov_b32_e32 v12, v229
	v_mov_b32_e32 v11, v230
	v_mov_b32_e32 v10, v231
	v_mov_b32_e32 v9, v232
	v_mov_b32_e32 v8, v233
	v_mov_b32_e32 v7, v234
	v_mov_b32_e32 v6, v235
	v_mov_b32_e32 v5, v236
	v_mov_b32_e32 v4, v237
	v_mov_b32_e32 v20, 0xff800000
	s_barrier
	s_and_saveexec_b64 s[20:21], s[2:3]
	ds_read_b32 v20, v188 offset:256
	s_or_b64 exec, exec, s[20:21]
	s_waitcnt vmcnt(15)
	v_cmp_lt_f32_e32 vcc, s45, v19
	s_nop 1
	v_cndmask_b32_e32 v1, 0, v19, vcc
	s_waitcnt vmcnt(14)
	v_cmp_lt_f32_e32 vcc, s45, v18
	v_add_f32_e32 v0, 0, v1
	v_mul_f32_e32 v3, v1, v1
	v_cndmask_b32_e32 v2, 0, v18, vcc
	s_waitcnt vmcnt(13)
	v_cmp_lt_f32_e32 vcc, s45, v17
	v_mul_f32_e32 v1, v2, v2
	v_pk_add_f32 v[0:1], v[0:1], v[2:3]
	v_cndmask_b32_e32 v22, 0, v17, vcc
	s_waitcnt vmcnt(12)
	v_cmp_lt_f32_e32 vcc, s45, v16
	v_mul_f32_e32 v23, v22, v22
	v_pk_add_f32 v[0:1], v[0:1], v[22:23]
	v_cndmask_b32_e32 v24, 0, v16, vcc
	s_waitcnt vmcnt(11)
	v_cmp_lt_f32_e32 vcc, s45, v15
	v_mul_f32_e32 v25, v24, v24
	v_pk_add_f32 v[0:1], v[0:1], v[24:25]
	v_cndmask_b32_e32 v26, 0, v15, vcc
	s_waitcnt vmcnt(10)
	v_cmp_lt_f32_e32 vcc, s45, v14
	v_mul_f32_e32 v27, v26, v26
	v_pk_add_f32 v[0:1], v[0:1], v[26:27]
	v_cndmask_b32_e32 v28, 0, v14, vcc
	s_waitcnt vmcnt(9)
	v_cmp_lt_f32_e32 vcc, s45, v13
	v_mul_f32_e32 v29, v28, v28
	v_pk_add_f32 v[0:1], v[0:1], v[28:29]
	v_cndmask_b32_e32 v30, 0, v13, vcc
	s_waitcnt vmcnt(8)
	v_cmp_lt_f32_e32 vcc, s45, v12
	v_mul_f32_e32 v31, v30, v30
	v_pk_add_f32 v[0:1], v[0:1], v[30:31]
	v_cndmask_b32_e32 v32, 0, v12, vcc
	s_waitcnt vmcnt(7)
	v_cmp_lt_f32_e32 vcc, s45, v11
	v_mul_f32_e32 v33, v32, v32
	v_pk_add_f32 v[0:1], v[0:1], v[32:33]
	v_cndmask_b32_e32 v34, 0, v11, vcc
	s_waitcnt vmcnt(6)
	v_cmp_lt_f32_e32 vcc, s45, v10
	v_mul_f32_e32 v35, v34, v34
	v_pk_add_f32 v[0:1], v[0:1], v[34:35]
	v_cndmask_b32_e32 v36, 0, v10, vcc
	s_waitcnt vmcnt(5)
	v_cmp_lt_f32_e32 vcc, s45, v9
	v_mul_f32_e32 v37, v36, v36
	v_pk_add_f32 v[0:1], v[0:1], v[36:37]
	v_cndmask_b32_e32 v38, 0, v9, vcc
	s_waitcnt vmcnt(4)
	v_cmp_lt_f32_e32 vcc, s45, v8
	v_mul_f32_e32 v39, v38, v38
	v_pk_add_f32 v[0:1], v[0:1], v[38:39]
	v_cndmask_b32_e32 v40, 0, v8, vcc
	s_waitcnt vmcnt(3)
	v_cmp_lt_f32_e32 vcc, s45, v7
	v_mul_f32_e32 v41, v40, v40
	v_pk_add_f32 v[0:1], v[0:1], v[40:41]
	v_cndmask_b32_e32 v2, 0, v7, vcc
	s_waitcnt vmcnt(2)
	v_cmp_lt_f32_e32 vcc, s45, v6
	v_mul_f32_e32 v3, v2, v2
	v_pk_add_f32 v[0:1], v[0:1], v[2:3]
	v_cndmask_b32_e32 v22, 0, v6, vcc
	s_waitcnt vmcnt(1)
	v_cmp_lt_f32_e32 vcc, s45, v5
	v_mul_f32_e32 v23, v22, v22
	v_pk_add_f32 v[0:1], v[0:1], v[22:23]
	v_cndmask_b32_e32 v24, 0, v5, vcc
	s_waitcnt vmcnt(0)
	v_cmp_lt_f32_e32 vcc, s45, v4
	v_mul_f32_e32 v25, v24, v24
	v_pk_add_f32 v[0:1], v[0:1], v[24:25]
	v_cndmask_b32_e32 v26, 0, v4, vcc
	s_waitcnt lgkmcnt(0)
	v_cmp_lt_f32_e32 vcc, s45, v20
	v_mul_f32_e32 v27, v26, v26
	v_pk_add_f32 v[0:1], v[0:1], v[26:27]
	v_cndmask_b32_e32 v28, 0, v20, vcc
	v_mul_f32_e32 v29, v28, v28
	v_pk_add_f32 v[0:1], v[0:1], v[28:29]
	s_nop 1
	v_add_f32_dpp v0, v0, v0 quad_perm:[1,0,3,2] row_mask:0xf bank_mask:0xf bound_ctrl:1
	v_add_f32_dpp v1, v1, v1 quad_perm:[1,0,3,2] row_mask:0xf bank_mask:0xf bound_ctrl:1
	s_nop 0
	v_add_f32_dpp v0, v0, v0 quad_perm:[2,3,0,1] row_mask:0xf bank_mask:0xf bound_ctrl:1
	v_add_f32_dpp v1, v1, v1 quad_perm:[2,3,0,1] row_mask:0xf bank_mask:0xf bound_ctrl:1
	s_nop 0
	v_add_f32_dpp v0, v0, v0 row_half_mirror row_mask:0xf bank_mask:0xf bound_ctrl:1
	v_add_f32_dpp v1, v1, v1 row_half_mirror row_mask:0xf bank_mask:0xf bound_ctrl:1
	s_nop 0
	v_add_f32_dpp v0, v0, v0 row_ror:8 row_mask:0xf bank_mask:0xf
	v_add_f32_dpp v1, v1, v1 row_ror:8 row_mask:0xf bank_mask:0xf
	s_nop 0
	v_readlane_b32 s98, v0, 16
	v_readlane_b32 s99, v1, 16
	v_readlane_b32 s100, v0, 32
	v_readlane_b32 s101, v1, 32
	v_readlane_b32 s20, v0, 48
	v_readlane_b32 s21, v1, 48
	v_add_f32_e32 v0, s98, v0
	v_add_f32_e32 v1, s99, v1
	v_mov_b32_e32 v2, s100
	v_mov_b32_e32 v3, s101
	v_add_f32_e32 v2, s20, v2
	v_add_f32_e32 v3, s21, v3
	s_and_saveexec_b64 s[20:21], s[0:1]
	s_cbranch_execz .LBB0_2338
	s_lshl_b32 s30, s55, 3
	s_add_i32 s30, s30, 0
	s_waitcnt lgkmcnt(0)
	v_pk_add_f32 v[0:1], v[0:1], v[2:3]
	v_mov_b32_e32 v2, s30
	ds_write_b64 v2, v[0:1]

.LBB0_2689:
	ds_read_b128 v[108:111], v94 offset:34816
	ds_read_b128 v[112:115], v98 offset:53248
	s_mov_b32 s38, 0xf800000
	s_waitcnt lgkmcnt(0)
	v_mfma_f32_32x32x16_bf16 v[0:15], v[108:111], v[112:115], v[0:15]
	ds_read_b128 v[108:111], v94 offset:39424
	s_waitcnt lgkmcnt(0)
	v_mfma_f32_32x32x16_bf16 v[16:31], v[108:111], v[112:115], v[16:31]
	ds_read_b128 v[108:111], v94 offset:34848
	ds_read_b128 v[112:115], v98 offset:53280
	s_waitcnt lgkmcnt(0)
	v_mfma_f32_32x32x16_bf16 v[0:15], v[108:111], v[112:115], v[0:15]
	ds_read_b128 v[108:111], v94 offset:39456
	s_waitcnt lgkmcnt(0)
	v_mfma_f32_32x32x16_bf16 v[16:31], v[108:111], v[112:115], v[16:31]
	ds_read_b128 v[108:111], v94 offset:34880
	ds_read_b128 v[112:115], v98 offset:53312
	s_waitcnt lgkmcnt(0)
	v_mfma_f32_32x32x16_bf16 v[0:15], v[108:111], v[112:115], v[0:15]
	ds_read_b128 v[108:111], v94 offset:39488
	s_waitcnt lgkmcnt(0)
	v_mfma_f32_32x32x16_bf16 v[16:31], v[108:111], v[112:115], v[16:31]
	ds_read_b128 v[108:111], v94 offset:34912
	ds_read_b128 v[112:115], v94 offset:39520
	s_waitcnt lgkmcnt(1)
	v_mfma_f32_32x32x16_bf16 v[0:15], v[108:111], v[72:75], v[0:15]
	ds_read_b128 v[108:111], v95
	ds_read_b128 v[116:119], v95 offset:32
	ds_read_b128 v[120:123], v95 offset:128
	s_waitcnt lgkmcnt(3)
	v_mfma_f32_32x32x16_bf16 v[16:31], v[112:115], v[72:75], v[16:31]
	ds_read_b128 v[72:75], v95 offset:160
	ds_read_b128 v[112:115], v95 offset:192
	s_waitcnt lgkmcnt(4)
	s_nop 3
	v_mul_f32_e64 v0, v0, v108
	v_mul_f32_e64 v1, v1, v109
	v_pk_mul_f32 v[2:3], v[2:3], v[110:111]
	ds_read_b128 v[108:111], v95 offset:64
	s_waitcnt lgkmcnt(4)
	v_pk_mul_f32 v[4:5], v[4:5], v[116:117]
	v_pk_mul_f32 v[6:7], v[6:7], v[118:119]
	s_waitcnt lgkmcnt(2)
	v_pk_mul_f32 v[20:21], v[20:21], v[72:73]
	v_pk_mul_f32 v[22:23], v[22:23], v[74:75]
	ds_read_b128 v[72:75], v95 offset:96
	ds_read_b128 v[116:119], v95 offset:224
	v_pk_mul_f32 v[16:17], v[16:17], v[120:121]
	v_pk_mul_f32 v[18:19], v[18:19], v[122:123]
	s_waitcnt lgkmcnt(2)
	v_pk_mul_f32 v[8:9], v[8:9], v[108:109]
	v_pk_mul_f32 v[10:11], v[10:11], v[110:111]
	s_waitcnt lgkmcnt(1)
	v_pk_mul_f32 v[12:13], v[12:13], v[72:73]
	v_pk_mul_f32 v[14:15], v[14:15], v[74:75]
	v_cvt_pk_bf16_f32 v72, v0, v1
	v_cvt_pk_bf16_f32 v73, v2, v3
	v_cvt_pk_bf16_f32 v108, v4, v5
	v_cvt_pk_bf16_f32 v109, v6, v7
	v_pk_mul_f32 v[24:25], v[24:25], v[112:113]
	v_pk_mul_f32 v[26:27], v[26:27], v[114:115]
	s_waitcnt lgkmcnt(0)
	v_pk_mul_f32 v[28:29], v[28:29], v[116:117]
	v_pk_mul_f32 v[30:31], v[30:31], v[118:119]
	v_cvt_pk_bf16_f32 v74, v16, v17
	v_cvt_pk_bf16_f32 v75, v18, v19
	v_cvt_pk_bf16_f32 v110, v20, v21
	v_cvt_pk_bf16_f32 v111, v22, v23
	ds_write2_b64 v89, v[72:73], v[108:109] offset1:2
	ds_write2_b64 v89, v[74:75], v[110:111] offset0:8 offset1:10
	v_cvt_pk_bf16_f32 v72, v8, v9
	v_cvt_pk_bf16_f32 v73, v10, v11
	v_cvt_pk_bf16_f32 v108, v12, v13
	v_cvt_pk_bf16_f32 v109, v14, v15
	v_cvt_pk_bf16_f32 v74, v24, v25
	v_cvt_pk_bf16_f32 v75, v26, v27
	v_cvt_pk_bf16_f32 v110, v28, v29
	v_cvt_pk_bf16_f32 v111, v30, v31
	ds_write2_b64 v89, v[72:73], v[108:109] offset0:4 offset1:6
	ds_write2_b64 v89, v[74:75], v[110:111] offset0:12 offset1:14
	ds_write2_b32 v96, v32, v33 offset1:132
	v_add_u32_e32 v32, 0x400, v96
	ds_write2_b32 v32, v34, v35 offset0:8 offset1:140
	v_add_u32_e32 v32, 0x1000, v96
	ds_write2_b32 v32, v36, v37 offset0:32 offset1:164
	v_add_u32_e32 v32, 0x1400, v96
	ds_write2_b32 v32, v38, v39 offset0:40 offset1:172
	v_add_u32_e32 v32, 0x2000, v96
	ds_write2_b32 v32, v40, v41 offset0:64 offset1:196
	v_add_u32_e32 v32, 0x2400, v96
	ds_write2_b32 v32, v42, v43 offset0:72 offset1:204
	v_add_u32_e32 v32, 0x3000, v96
	ds_write2_b32 v32, v44, v45 offset0:96 offset1:228
	v_add_u32_e32 v32, 0x3400, v96
	ds_write2_b32 v32, v46, v47 offset0:104 offset1:236
	s_waitcnt lgkmcnt(0)
	s_barrier
	ds_read_b128 v[32:35], v163
	ds_read_b128 v[36:39], v163 offset:16
	ds_read_b128 v[40:43], v163 offset:32
	ds_read_b128 v[44:47], v163 offset:48
	s_waitcnt lgkmcnt(3)
	v_pk_mul_f32 v[72:73], v[34:35], v[34:35]
	v_pk_mul_f32 v[74:75], v[32:33], v[32:33]
	s_waitcnt lgkmcnt(0)
	v_mul_f32_e32 v107, v44, v44
	v_pk_mov_b32 v[108:109], v[74:75], v[72:73] op_sel:[1,0]
	v_mov_b32_e32 v75, v73
	v_pk_add_f32 v[72:73], v[108:109], v[74:75]
	v_pk_mul_f32 v[74:75], v[38:39], v[38:39]
	v_pk_mul_f32 v[108:109], v[36:37], v[36:37]
	v_pk_add_f32 v[72:73], v[72:73], v[72:73] op_sel:[0,1] op_sel_hi:[1,0]
	v_pk_mov_b32 v[110:111], v[108:109], v[74:75] op_sel:[1,0]
	v_mov_b32_e32 v109, v75
	v_pk_add_f32 v[74:75], v[110:111], v[108:109]
	v_mul_f32_e32 v108, v45, v45
	v_pk_add_f32 v[74:75], v[74:75], v[74:75] op_sel:[0,1] op_sel_hi:[1,0]
	v_mov_b32_e32 v73, v107
	v_mov_b32_e32 v75, v108
	v_pk_add_f32 v[72:73], v[72:73], v[74:75]
	v_mul_f32_e32 v74, v41, v41
	v_mul_f32_e32 v109, v46, v46
	v_pk_fma_f32 v[74:75], v[40:41], v[40:41], v[74:75] op_sel_hi:[1,1,0]
	v_mul_f32_e32 v108, v43, v43
	v_mul_f32_e32 v110, v47, v47
	v_mov_b32_e32 v75, v109
	v_pk_fma_f32 v[108:109], v[42:43], v[42:43], v[108:109] op_sel_hi:[1,1,0]
	s_nop 0
	v_mov_b32_e32 v109, v110
	v_pk_add_f32 v[74:75], v[74:75], v[108:109]
	s_nop 0
	v_pk_add_f32 v[72:73], v[72:73], v[74:75]
	s_nop 0
	v_add_f32_e32 v72, v72, v73
	s_nop 1
	v_add_f32_dpp v72, v72, v72 quad_perm:[1,0,3,2] row_mask:0xf bank_mask:0xf bound_ctrl:1
	s_nop 1
	v_add_f32_dpp v72, v72, v72 quad_perm:[2,3,0,1] row_mask:0xf bank_mask:0xf bound_ctrl:1
	s_nop 1
	v_add_f32_dpp v72, v72, v72 row_half_mirror row_mask:0xf bank_mask:0xf bound_ctrl:1
	v_fmamk_f32 v72, v72, 0x3c000000, v178
	v_cmp_gt_f32_e32 vcc, s38, v72
	v_mul_f32_e32 v73, 0x4f800000, v72
	s_nop 0
	v_cndmask_b32_e32 v72, v72, v73, vcc
	v_sqrt_f32_e32 v73, v72
	s_nop 0
	v_add_u32_e32 v74, -1, v73
	v_fma_f32 v75, -v74, v73, v72
	v_cmp_ge_f32_e64 s[38:39], 0, v75
	v_add_u32_e32 v75, 1, v73
	s_nop 0
	v_cndmask_b32_e64 v74, v73, v74, s[38:39]
	v_fma_f32 v73, -v75, v73, v72
	v_cmp_lt_f32_e64 s[38:39], 0, v73
	s_nop 1
	v_cndmask_b32_e64 v73, v74, v75, s[38:39]
	v_mul_f32_e32 v74, 0x37800000, v73
	v_cndmask_b32_e32 v73, v73, v74, vcc
	v_cmp_class_f32_e32 vcc, v72, v179
	s_nop 1
	v_cndmask_b32_e32 v72, v73, v72, vcc
	v_div_scale_f32 v73, s[38:39], v72, v72, 1.0
	v_rcp_f32_e32 v74, v73
	s_nop 0
	v_fma_f32 v75, -v73, v74, 1.0
	v_fmac_f32_e32 v74, v75, v74
	v_div_scale_f32 v75, vcc, 1.0, v72, 1.0
	v_mul_f32_e32 v107, v75, v74
	v_fma_f32 v108, -v73, v107, v75
	v_fmac_f32_e32 v107, v108, v74
	v_fma_f32 v73, -v73, v107, v75
	v_div_fmas_f32 v73, v73, v74, v107
	v_div_fixup_f32 v72, v73, v72, 1.0
	v_pk_mul_f32 v[32:33], v[32:33], v[72:73] op_sel_hi:[1,0]
	s_waitcnt vmcnt(1)
	v_lshlrev_b32_e32 v74, 16, v52
	v_and_b32_e32 v75, 0xffff0000, v52
	s_waitcnt vmcnt(0)
	v_pk_mul_f32 v[32:33], v[68:69], v[32:33]
	v_pk_mul_f32 v[34:35], v[34:35], v[72:73] op_sel_hi:[1,0]
	v_pk_mul_f32 v[32:33], v[32:33], v[74:75]
	v_lshlrev_b32_e32 v74, 16, v53
	v_and_b32_e32 v75, 0xffff0000, v53
	v_pk_mul_f32 v[34:35], v[70:71], v[34:35]
	v_pk_mul_f32 v[36:37], v[36:37], v[72:73] op_sel_hi:[1,0]
	v_pk_mul_f32 v[34:35], v[34:35], v[74:75]
	v_cvt_pk_bf16_f32 v32, v32, v33
	v_cvt_pk_bf16_f32 v33, v34, v35
	v_lshlrev_b32_e32 v34, 16, v54
	v_and_b32_e32 v35, 0xffff0000, v54
	v_pk_mul_f32 v[36:37], v[64:65], v[36:37]
	v_pk_mul_f32 v[38:39], v[38:39], v[72:73] op_sel_hi:[1,0]
	v_pk_mul_f32 v[34:35], v[36:37], v[34:35]
	v_lshlrev_b32_e32 v36, 16, v55
	v_and_b32_e32 v37, 0xffff0000, v55
	v_pk_mul_f32 v[38:39], v[66:67], v[38:39]
	v_cvt_pk_bf16_f32 v34, v34, v35
	v_pk_mul_f32 v[36:37], v[38:39], v[36:37]
	v_pk_mul_f32 v[38:39], v[40:41], v[72:73] op_sel_hi:[1,0]
	v_cvt_pk_bf16_f32 v35, v36, v37
	v_lshlrev_b32_e32 v36, 16, v48
	v_and_b32_e32 v37, 0xffff0000, v48
	v_pk_mul_f32 v[38:39], v[60:61], v[38:39]
	v_pk_mul_f32 v[40:41], v[42:43], v[72:73] op_sel_hi:[1,0]
	v_pk_mul_f32 v[36:37], v[38:39], v[36:37]
	v_lshlrev_b32_e32 v38, 16, v49
	v_and_b32_e32 v39, 0xffff0000, v49
	v_pk_mul_f32 v[40:41], v[62:63], v[40:41]
	v_cvt_pk_bf16_f32 v36, v36, v37
	v_pk_mul_f32 v[38:39], v[40:41], v[38:39]
	v_pk_mul_f32 v[40:41], v[44:45], v[72:73] op_sel_hi:[1,0]
	v_cvt_pk_bf16_f32 v37, v38, v39
	v_lshlrev_b32_e32 v38, 16, v50
	v_and_b32_e32 v39, 0xffff0000, v50
	v_pk_mul_f32 v[40:41], v[56:57], v[40:41]
	v_pk_mul_f32 v[42:43], v[46:47], v[72:73] op_sel_hi:[1,0]
	v_pk_mul_f32 v[38:39], v[40:41], v[38:39]
	v_lshlrev_b32_e32 v40, 16, v51
	v_and_b32_e32 v41, 0xffff0000, v51
	v_pk_mul_f32 v[42:43], v[58:59], v[42:43]
	v_cvt_pk_bf16_f32 v38, v38, v39
	v_pk_mul_f32 v[40:41], v[42:43], v[40:41]
	s_nop 0
	v_cvt_pk_bf16_f32 v39, v40, v41
	v_lshl_add_u64 v[40:41], s[42:43], 0, v[78:79]
	v_add_co_u32_e32 v40, vcc, 0x10400000, v40
	s_nop 1
	v_addc_co_u32_e32 v41, vcc, 0, v41, vcc
	s_andn2_b64 vcc, exec, s[70:71]
	global_store_dwordx4 v[40:41], v[32:35], off
	global_store_dwordx4 v[40:41], v[36:39], off offset:16
	s_cbranch_vccnz .LBB0_2664
	v_lshl_add_u64 v[32:33], s[42:43], 0, v[76:77]
	s_mov_b64 s[38:39], 0x5310000
	v_lshl_add_u64 v[34:35], v[32:33], 0, s[38:39]
	v_add_co_u32_e32 v32, vcc, 0x5310000, v32
	s_nop 1
	v_addc_co_u32_e32 v33, vcc, 0, v33, vcc
	global_load_dwordx4 v[52:55], v[32:33], off
	global_load_dwordx4 v[48:51], v[34:35], off offset:16
	s_branch .LBB0_2664

.LBB0_2703:
	s_bfe_u32 s23, s58, 0x50003
	v_mbcnt_lo_u32_b32 v241, -1, 0
	v_mbcnt_hi_u32_b32 v241, -1, v241
	v_lshlrev_b32_e32 v241, 2, v241
	v_lshl_or_b32 v241, s23, 8, v241
	global_load_dword v240, v241, s[28:29]
	s_lshl_b32 s61, s23, 3
	s_and_b32 s22, s58, 7
	s_or_b32 s20, s61, 0x4000
	v_readfirstlane_b32 s59, v149
	s_or_b32 s60, s20, s22
	s_add_i32 s20, s59, s20
	s_ashr_i32 s21, s20, 31
	s_lshl_b32 s30, s60, 11
	s_lshl_b64 s[20:21], s[20:21], 7
	v_lshl_add_u64 v[4:5], v[140:141], 0, s[30:31]
	v_lshl_add_u64 v[12:13], v[142:143], 0, s[20:21]
	global_load_dwordx4 v[0:3], v[4:5], off
	s_nop 0
	global_load_dwordx4 v[4:7], v[4:5], off offset:16
	s_nop 0
	global_load_dwordx4 v[8:11], v[12:13], off
	s_nop 0
	global_load_dwordx4 v[12:15], v[12:13], off offset:16
	s_lshl_b32 s30, s60, 6
	v_lshl_add_u64 v[16:17], v[144:145], 0, s[30:31]
	global_load_dword v16, v[16:17], off
	s_and_b32 s20, s58, 0xff
	s_mul_i32 s30, s20, 0x8100
	v_lshl_add_u64 v[244:245], v[146:147], 0, s[30:31]
	global_load_dword v222, v[244:245], off
	global_load_dword v223, v[244:245], off offset:2048
	v_add_co_u32_e32 v246, vcc, 0x1000, v244
	s_nop 1
	v_addc_co_u32_e32 v247, vcc, 0, v245, vcc
	global_load_dword v224, v[246:247], off
	global_load_dword v225, v[246:247], off offset:2048
	v_add_co_u32_e32 v246, vcc, 0x2000, v244
	s_nop 1
	v_addc_co_u32_e32 v247, vcc, 0, v245, vcc
	global_load_dword v226, v[246:247], off
	global_load_dword v227, v[246:247], off offset:2048
	v_add_co_u32_e32 v246, vcc, 0x3000, v244
	s_nop 1
	v_addc_co_u32_e32 v247, vcc, 0, v245, vcc
	global_load_dword v228, v[246:247], off
	global_load_dword v229, v[246:247], off offset:2048
	v_add_co_u32_e32 v246, vcc, 0x4000, v244
	s_nop 1
	v_addc_co_u32_e32 v247, vcc, 0, v245, vcc
	global_load_dword v230, v[246:247], off
	global_load_dword v231, v[246:247], off offset:2048
	v_add_co_u32_e32 v246, vcc, 0x5000, v244
	s_nop 1
	v_addc_co_u32_e32 v247, vcc, 0, v245, vcc
	global_load_dword v232, v[246:247], off
	global_load_dword v233, v[246:247], off offset:2048
	v_add_co_u32_e32 v246, vcc, 0x6000, v244
	s_nop 1
	v_addc_co_u32_e32 v247, vcc, 0, v245, vcc
	global_load_dword v234, v[246:247], off
	global_load_dword v235, v[246:247], off offset:2048
	v_add_co_u32_e32 v246, vcc, 0x7000, v244
	s_nop 1
	v_addc_co_u32_e32 v247, vcc, 0, v245, vcc
	global_load_dword v236, v[246:247], off
	global_load_dword v237, v[246:247], off offset:2048
	s_waitcnt vmcnt(20)
	v_lshlrev_b32_e32 v17, 16, v0
	s_waitcnt vmcnt(18)
	v_lshlrev_b32_e32 v25, 16, v8
	v_and_b32_e32 v0, 0xffff0000, v0
	v_and_b32_e32 v8, 0xffff0000, v8
	v_fma_f32 v17, v17, v25, 0
	v_lshlrev_b32_e32 v18, 16, v1
	v_lshlrev_b32_e32 v26, 16, v9
	v_fmac_f32_e32 v17, v0, v8
	v_and_b32_e32 v1, 0xffff0000, v1
	v_and_b32_e32 v9, 0xffff0000, v9
	v_fmac_f32_e32 v17, v18, v26
	v_lshlrev_b32_e32 v19, 16, v2
	v_lshlrev_b32_e32 v27, 16, v10
	v_fmac_f32_e32 v17, v1, v9
	v_and_b32_e32 v2, 0xffff0000, v2
	v_and_b32_e32 v10, 0xffff0000, v10
	v_fmac_f32_e32 v17, v19, v27
	v_lshlrev_b32_e32 v20, 16, v3
	v_lshlrev_b32_e32 v28, 16, v11
	v_fmac_f32_e32 v17, v2, v10
	v_and_b32_e32 v3, 0xffff0000, v3
	v_and_b32_e32 v11, 0xffff0000, v11
	v_fmac_f32_e32 v17, v20, v28
	v_lshlrev_b32_e32 v21, 16, v4
	s_waitcnt vmcnt(17)
	v_lshlrev_b32_e32 v29, 16, v12
	v_fmac_f32_e32 v17, v3, v11
	v_and_b32_e32 v4, 0xffff0000, v4
	v_and_b32_e32 v12, 0xffff0000, v12
	v_fmac_f32_e32 v17, v21, v29
	v_lshlrev_b32_e32 v22, 16, v5
	v_lshlrev_b32_e32 v30, 16, v13
	v_fmac_f32_e32 v17, v4, v12
	v_and_b32_e32 v5, 0xffff0000, v5
	v_and_b32_e32 v13, 0xffff0000, v13
	v_fmac_f32_e32 v17, v22, v30
	v_lshlrev_b32_e32 v23, 16, v6
	v_lshlrev_b32_e32 v31, 16, v14
	v_fmac_f32_e32 v17, v5, v13
	v_and_b32_e32 v6, 0xffff0000, v6
	v_and_b32_e32 v14, 0xffff0000, v14
	v_fmac_f32_e32 v17, v23, v31
	v_lshlrev_b32_e32 v24, 16, v7
	v_lshlrev_b32_e32 v32, 16, v15
	v_fmac_f32_e32 v17, v6, v14
	v_and_b32_e32 v7, 0xffff0000, v7
	v_fmac_f32_e32 v17, v24, v32
	v_and_b32_e32 v0, 0xffff0000, v15
	v_fmac_f32_e32 v17, v7, v0
	s_nop 1
	v_add_f32_dpp v0, v17, v17 quad_perm:[1,0,3,2] row_mask:0xf bank_mask:0xf bound_ctrl:1
	s_nop 1
	v_add_f32_dpp v0, v0, v0 quad_perm:[2,3,0,1] row_mask:0xf bank_mask:0xf bound_ctrl:1
	v_max_f32_e32 v0, 0, v0
	s_waitcnt vmcnt(16)
	v_mul_f32_e32 v1, v16, v0
	s_nop 1
	v_mov_b32_dpp v1, v1 row_half_mirror row_mask:0xf bank_mask:0xf bound_ctrl:1
	v_fmac_f32_e32 v1, v16, v0
	s_nop 1
	v_add_f32_dpp v0, v1, v1 row_ror:8 row_mask:0xf bank_mask:0xf
	s_nop 0
	v_readlane_b32 s98, v0, 16
	v_readlane_b32 s99, v0, 32
	v_readlane_b32 s100, v0, 48
	s_nop 1
	v_add_f32_e32 v0, s98, v0
	v_mov_b32_e32 v1, s99
	v_add_f32_e32 v1, s100, v1
	s_and_saveexec_b64 s[20:21], s[0:1]
	s_cbranch_execz .LBB0_2705
	s_cmp_le_i32 s59, s22
	s_cselect_b64 vcc, -1, 0
	s_lshl_b32 s30, s59, 2
	s_waitcnt lgkmcnt(0)
	v_add_f32_e32 v0, v0, v1
	s_add_i32 s30, s30, 0
	v_cndmask_b32_e32 v0, v217, v0, vcc
	v_mov_b32_e32 v1, s30
	ds_write_b32 v1, v0 offset:256
.LBB0_2705:
	s_or_b64 exec, exec, s[20:21]
	s_waitcnt vmcnt(0) lgkmcnt(0)
	v_mov_b32_e32 v19, v222
	v_mov_b32_e32 v18, v223
	v_mov_b32_e32 v17, v224
	v_mov_b32_e32 v16, v225
	v_mov_b32_e32 v15, v226
	v_mov_b32_e32 v14, v227
	v_mov_b32_e32 v13, v228
	v_mov_b32_e32 v12, v229
	v_mov_b32_e32 v11, v230
	v_mov_b32_e32 v10, v231
	v_mov_b32_e32 v9, v232
	v_mov_b32_e32 v8, v233
	v_mov_b32_e32 v7, v234
	v_mov_b32_e32 v6, v235
	v_mov_b32_e32 v5, v236
	v_mov_b32_e32 v4, v237
	v_mov_b32_e32 v20, 0xff800000
	s_barrier
	s_and_saveexec_b64 s[20:21], s[2:3]
	ds_read_b32 v20, v188 offset:256
	s_or_b64 exec, exec, s[20:21]
	s_waitcnt vmcnt(15)
	v_cmp_lt_f32_e32 vcc, s47, v19
	s_nop 1
	v_cndmask_b32_e32 v1, 0, v19, vcc
	s_waitcnt vmcnt(14)
	v_cmp_lt_f32_e32 vcc, s47, v18
	v_add_f32_e32 v0, 0, v1
	v_mul_f32_e32 v3, v1, v1
	v_cndmask_b32_e32 v2, 0, v18, vcc
	s_waitcnt vmcnt(13)
	v_cmp_lt_f32_e32 vcc, s47, v17
	v_mul_f32_e32 v1, v2, v2
	v_pk_add_f32 v[0:1], v[0:1], v[2:3]
	v_cndmask_b32_e32 v22, 0, v17, vcc
	s_waitcnt vmcnt(12)
	v_cmp_lt_f32_e32 vcc, s47, v16
	v_mul_f32_e32 v23, v22, v22
	v_pk_add_f32 v[0:1], v[0:1], v[22:23]
	v_cndmask_b32_e32 v24, 0, v16, vcc
	s_waitcnt vmcnt(11)
	v_cmp_lt_f32_e32 vcc, s47, v15
	v_mul_f32_e32 v25, v24, v24
	v_pk_add_f32 v[0:1], v[0:1], v[24:25]
	v_cndmask_b32_e32 v26, 0, v15, vcc
	s_waitcnt vmcnt(10)
	v_cmp_lt_f32_e32 vcc, s47, v14
	v_mul_f32_e32 v27, v26, v26
	v_pk_add_f32 v[0:1], v[0:1], v[26:27]
	v_cndmask_b32_e32 v28, 0, v14, vcc
	s_waitcnt vmcnt(9)
	v_cmp_lt_f32_e32 vcc, s47, v13
	v_mul_f32_e32 v29, v28, v28
	v_pk_add_f32 v[0:1], v[0:1], v[28:29]
	v_cndmask_b32_e32 v30, 0, v13, vcc
	s_waitcnt vmcnt(8)
	v_cmp_lt_f32_e32 vcc, s47, v12
	v_mul_f32_e32 v31, v30, v30
	v_pk_add_f32 v[0:1], v[0:1], v[30:31]
	v_cndmask_b32_e32 v32, 0, v12, vcc
	s_waitcnt vmcnt(7)
	v_cmp_lt_f32_e32 vcc, s47, v11
	v_mul_f32_e32 v33, v32, v32
	v_pk_add_f32 v[0:1], v[0:1], v[32:33]
	v_cndmask_b32_e32 v34, 0, v11, vcc
	s_waitcnt vmcnt(6)
	v_cmp_lt_f32_e32 vcc, s47, v10
	v_mul_f32_e32 v35, v34, v34
	v_pk_add_f32 v[0:1], v[0:1], v[34:35]
	v_cndmask_b32_e32 v36, 0, v10, vcc
	s_waitcnt vmcnt(5)
	v_cmp_lt_f32_e32 vcc, s47, v9
	v_mul_f32_e32 v37, v36, v36
	v_pk_add_f32 v[0:1], v[0:1], v[36:37]
	v_cndmask_b32_e32 v38, 0, v9, vcc
	s_waitcnt vmcnt(4)
	v_cmp_lt_f32_e32 vcc, s47, v8
	v_mul_f32_e32 v39, v38, v38
	v_pk_add_f32 v[0:1], v[0:1], v[38:39]
	v_cndmask_b32_e32 v40, 0, v8, vcc
	s_waitcnt vmcnt(3)
	v_cmp_lt_f32_e32 vcc, s47, v7
	v_mul_f32_e32 v41, v40, v40
	v_pk_add_f32 v[0:1], v[0:1], v[40:41]
	v_cndmask_b32_e32 v2, 0, v7, vcc
	s_waitcnt vmcnt(2)
	v_cmp_lt_f32_e32 vcc, s47, v6
	v_mul_f32_e32 v3, v2, v2
	v_pk_add_f32 v[0:1], v[0:1], v[2:3]
	v_cndmask_b32_e32 v22, 0, v6, vcc
	s_waitcnt vmcnt(1)
	v_cmp_lt_f32_e32 vcc, s47, v5
	v_mul_f32_e32 v23, v22, v22
	v_pk_add_f32 v[0:1], v[0:1], v[22:23]
	v_cndmask_b32_e32 v24, 0, v5, vcc
	s_waitcnt vmcnt(0)
	v_cmp_lt_f32_e32 vcc, s47, v4
	v_mul_f32_e32 v25, v24, v24
	v_pk_add_f32 v[0:1], v[0:1], v[24:25]
	v_cndmask_b32_e32 v26, 0, v4, vcc
	s_waitcnt lgkmcnt(0)
	v_cmp_lt_f32_e32 vcc, s47, v20
	v_mul_f32_e32 v27, v26, v26
	v_pk_add_f32 v[0:1], v[0:1], v[26:27]
	v_cndmask_b32_e32 v28, 0, v20, vcc
	v_mul_f32_e32 v29, v28, v28
	v_pk_add_f32 v[0:1], v[0:1], v[28:29]
	s_nop 1
	v_add_f32_dpp v0, v0, v0 quad_perm:[1,0,3,2] row_mask:0xf bank_mask:0xf bound_ctrl:1
	v_add_f32_dpp v1, v1, v1 quad_perm:[1,0,3,2] row_mask:0xf bank_mask:0xf bound_ctrl:1
	s_nop 0
	v_add_f32_dpp v0, v0, v0 quad_perm:[2,3,0,1] row_mask:0xf bank_mask:0xf bound_ctrl:1
	v_add_f32_dpp v1, v1, v1 quad_perm:[2,3,0,1] row_mask:0xf bank_mask:0xf bound_ctrl:1
	s_nop 0
	v_add_f32_dpp v0, v0, v0 row_half_mirror row_mask:0xf bank_mask:0xf bound_ctrl:1
	v_add_f32_dpp v1, v1, v1 row_half_mirror row_mask:0xf bank_mask:0xf bound_ctrl:1
	s_nop 0
	v_add_f32_dpp v0, v0, v0 row_ror:8 row_mask:0xf bank_mask:0xf
	v_add_f32_dpp v1, v1, v1 row_ror:8 row_mask:0xf bank_mask:0xf
	s_nop 0
	v_readlane_b32 s98, v0, 16
	v_readlane_b32 s99, v1, 16
	v_readlane_b32 s100, v0, 32
	v_readlane_b32 s101, v1, 32
	v_readlane_b32 s20, v0, 48
	v_readlane_b32 s21, v1, 48
	v_add_f32_e32 v0, s98, v0
	v_add_f32_e32 v1, s99, v1
	v_mov_b32_e32 v2, s100
	v_mov_b32_e32 v3, s101
	v_add_f32_e32 v2, s20, v2
	v_add_f32_e32 v3, s21, v3
	s_and_saveexec_b64 s[20:21], s[0:1]
	s_cbranch_execz .LBB0_2709
	s_lshl_b32 s30, s59, 3
	s_add_i32 s30, s30, 0
	s_waitcnt lgkmcnt(0)
	v_pk_add_f32 v[0:1], v[0:1], v[2:3]
	v_mov_b32_e32 v2, s30
	ds_write_b64 v2, v[0:1]

.LBB0_3061:
	ds_read_b128 v[108:111], v94 offset:34816
	ds_read_b128 v[112:115], v98 offset:53248
	s_mov_b32 s38, 0xf800000
	s_waitcnt lgkmcnt(0)
	v_mfma_f32_32x32x16_bf16 v[0:15], v[108:111], v[112:115], v[0:15]
	ds_read_b128 v[108:111], v94 offset:39424
	s_waitcnt lgkmcnt(0)
	v_mfma_f32_32x32x16_bf16 v[16:31], v[108:111], v[112:115], v[16:31]
	ds_read_b128 v[108:111], v94 offset:34848
	ds_read_b128 v[112:115], v98 offset:53280
	s_waitcnt lgkmcnt(0)
	v_mfma_f32_32x32x16_bf16 v[0:15], v[108:111], v[112:115], v[0:15]
	ds_read_b128 v[108:111], v94 offset:39456
	s_waitcnt lgkmcnt(0)
	v_mfma_f32_32x32x16_bf16 v[16:31], v[108:111], v[112:115], v[16:31]
	ds_read_b128 v[108:111], v94 offset:34880
	ds_read_b128 v[112:115], v98 offset:53312
	s_waitcnt lgkmcnt(0)
	v_mfma_f32_32x32x16_bf16 v[0:15], v[108:111], v[112:115], v[0:15]
	ds_read_b128 v[108:111], v94 offset:39488
	s_waitcnt lgkmcnt(0)
	v_mfma_f32_32x32x16_bf16 v[16:31], v[108:111], v[112:115], v[16:31]
	ds_read_b128 v[108:111], v94 offset:34912
	ds_read_b128 v[112:115], v94 offset:39520
	s_waitcnt lgkmcnt(1)
	v_mfma_f32_32x32x16_bf16 v[0:15], v[108:111], v[72:75], v[0:15]
	ds_read_b128 v[108:111], v95
	ds_read_b128 v[116:119], v95 offset:32
	ds_read_b128 v[120:123], v95 offset:128
	s_waitcnt lgkmcnt(3)
	v_mfma_f32_32x32x16_bf16 v[16:31], v[112:115], v[72:75], v[16:31]
	ds_read_b128 v[72:75], v95 offset:160
	ds_read_b128 v[112:115], v95 offset:192
	s_waitcnt lgkmcnt(4)
	s_nop 3
	v_mul_f32_e64 v0, v0, v108
	v_mul_f32_e64 v1, v1, v109
	v_pk_mul_f32 v[2:3], v[2:3], v[110:111]
	ds_read_b128 v[108:111], v95 offset:64
	s_waitcnt lgkmcnt(4)
	v_pk_mul_f32 v[4:5], v[4:5], v[116:117]
	v_pk_mul_f32 v[6:7], v[6:7], v[118:119]
	s_waitcnt lgkmcnt(2)
	v_pk_mul_f32 v[20:21], v[20:21], v[72:73]
	v_pk_mul_f32 v[22:23], v[22:23], v[74:75]
	ds_read_b128 v[72:75], v95 offset:96
	ds_read_b128 v[116:119], v95 offset:224
	v_pk_mul_f32 v[16:17], v[16:17], v[120:121]
	v_pk_mul_f32 v[18:19], v[18:19], v[122:123]
	s_waitcnt lgkmcnt(2)
	v_pk_mul_f32 v[8:9], v[8:9], v[108:109]
	v_pk_mul_f32 v[10:11], v[10:11], v[110:111]
	s_waitcnt lgkmcnt(1)
	v_pk_mul_f32 v[12:13], v[12:13], v[72:73]
	v_pk_mul_f32 v[14:15], v[14:15], v[74:75]
	v_cvt_pk_bf16_f32 v72, v0, v1
	v_cvt_pk_bf16_f32 v73, v2, v3
	v_cvt_pk_bf16_f32 v108, v4, v5
	v_cvt_pk_bf16_f32 v109, v6, v7
	v_pk_mul_f32 v[24:25], v[24:25], v[112:113]
	v_pk_mul_f32 v[26:27], v[26:27], v[114:115]
	s_waitcnt lgkmcnt(0)
	v_pk_mul_f32 v[28:29], v[28:29], v[116:117]
	v_pk_mul_f32 v[30:31], v[30:31], v[118:119]
	v_cvt_pk_bf16_f32 v74, v16, v17
	v_cvt_pk_bf16_f32 v75, v18, v19
	v_cvt_pk_bf16_f32 v110, v20, v21
	v_cvt_pk_bf16_f32 v111, v22, v23
	ds_write2_b64 v89, v[72:73], v[108:109] offset1:2
	ds_write2_b64 v89, v[74:75], v[110:111] offset0:8 offset1:10
	v_cvt_pk_bf16_f32 v72, v8, v9
	v_cvt_pk_bf16_f32 v73, v10, v11
	v_cvt_pk_bf16_f32 v108, v12, v13
	v_cvt_pk_bf16_f32 v109, v14, v15
	v_cvt_pk_bf16_f32 v74, v24, v25
	v_cvt_pk_bf16_f32 v75, v26, v27
	v_cvt_pk_bf16_f32 v110, v28, v29
	v_cvt_pk_bf16_f32 v111, v30, v31
	ds_write2_b64 v89, v[72:73], v[108:109] offset0:4 offset1:6
	ds_write2_b64 v89, v[74:75], v[110:111] offset0:12 offset1:14
	ds_write2_b32 v96, v32, v33 offset1:132
	v_add_u32_e32 v32, 0x400, v96
	ds_write2_b32 v32, v34, v35 offset0:8 offset1:140
	v_add_u32_e32 v32, 0x1000, v96
	ds_write2_b32 v32, v36, v37 offset0:32 offset1:164
	v_add_u32_e32 v32, 0x1400, v96
	ds_write2_b32 v32, v38, v39 offset0:40 offset1:172
	v_add_u32_e32 v32, 0x2000, v96
	ds_write2_b32 v32, v40, v41 offset0:64 offset1:196
	v_add_u32_e32 v32, 0x2400, v96
	ds_write2_b32 v32, v42, v43 offset0:72 offset1:204
	v_add_u32_e32 v32, 0x3000, v96
	ds_write2_b32 v32, v44, v45 offset0:96 offset1:228
	v_add_u32_e32 v32, 0x3400, v96
	ds_write2_b32 v32, v46, v47 offset0:104 offset1:236
	s_waitcnt lgkmcnt(0)
	s_barrier
	ds_read_b128 v[32:35], v163
	ds_read_b128 v[36:39], v163 offset:16
	ds_read_b128 v[40:43], v163 offset:32
	ds_read_b128 v[44:47], v163 offset:48
	s_waitcnt lgkmcnt(3)
	v_pk_mul_f32 v[72:73], v[34:35], v[34:35]
	v_pk_mul_f32 v[74:75], v[32:33], v[32:33]
	s_waitcnt lgkmcnt(0)
	v_mul_f32_e32 v107, v44, v44
	v_pk_mov_b32 v[108:109], v[74:75], v[72:73] op_sel:[1,0]
	v_mov_b32_e32 v75, v73
	v_pk_add_f32 v[72:73], v[108:109], v[74:75]
	v_pk_mul_f32 v[74:75], v[38:39], v[38:39]
	v_pk_mul_f32 v[108:109], v[36:37], v[36:37]
	v_pk_add_f32 v[72:73], v[72:73], v[72:73] op_sel:[0,1] op_sel_hi:[1,0]
	v_pk_mov_b32 v[110:111], v[108:109], v[74:75] op_sel:[1,0]
	v_mov_b32_e32 v109, v75
	v_pk_add_f32 v[74:75], v[110:111], v[108:109]
	v_mul_f32_e32 v108, v45, v45
	v_pk_add_f32 v[74:75], v[74:75], v[74:75] op_sel:[0,1] op_sel_hi:[1,0]
	v_mov_b32_e32 v73, v107
	v_mov_b32_e32 v75, v108
	v_pk_add_f32 v[72:73], v[72:73], v[74:75]
	v_mul_f32_e32 v74, v41, v41
	v_mul_f32_e32 v109, v46, v46
	v_pk_fma_f32 v[74:75], v[40:41], v[40:41], v[74:75] op_sel_hi:[1,1,0]
	v_mul_f32_e32 v108, v43, v43
	v_mul_f32_e32 v110, v47, v47
	v_mov_b32_e32 v75, v109
	v_pk_fma_f32 v[108:109], v[42:43], v[42:43], v[108:109] op_sel_hi:[1,1,0]
	s_nop 0
	v_mov_b32_e32 v109, v110
	v_pk_add_f32 v[74:75], v[74:75], v[108:109]
	s_nop 0
	v_pk_add_f32 v[72:73], v[72:73], v[74:75]
	s_nop 0
	v_add_f32_e32 v72, v72, v73
	s_nop 1
	v_add_f32_dpp v72, v72, v72 quad_perm:[1,0,3,2] row_mask:0xf bank_mask:0xf bound_ctrl:1
	s_nop 1
	v_add_f32_dpp v72, v72, v72 quad_perm:[2,3,0,1] row_mask:0xf bank_mask:0xf bound_ctrl:1
	s_nop 1
	v_add_f32_dpp v72, v72, v72 row_half_mirror row_mask:0xf bank_mask:0xf bound_ctrl:1
	v_fmamk_f32 v72, v72, 0x3c000000, v178
	v_cmp_gt_f32_e32 vcc, s38, v72
	v_mul_f32_e32 v73, 0x4f800000, v72
	s_nop 0
	v_cndmask_b32_e32 v72, v72, v73, vcc
	v_sqrt_f32_e32 v73, v72
	s_nop 0
	v_add_u32_e32 v74, -1, v73
	v_fma_f32 v75, -v74, v73, v72
	v_cmp_ge_f32_e64 s[38:39], 0, v75
	v_add_u32_e32 v75, 1, v73
	s_nop 0
	v_cndmask_b32_e64 v74, v73, v74, s[38:39]
	v_fma_f32 v73, -v75, v73, v72
	v_cmp_lt_f32_e64 s[38:39], 0, v73
	s_nop 1
	v_cndmask_b32_e64 v73, v74, v75, s[38:39]
	v_mul_f32_e32 v74, 0x37800000, v73
	v_cndmask_b32_e32 v73, v73, v74, vcc
	v_cmp_class_f32_e32 vcc, v72, v179
	s_nop 1
	v_cndmask_b32_e32 v72, v73, v72, vcc
	v_div_scale_f32 v73, s[38:39], v72, v72, 1.0
	v_rcp_f32_e32 v74, v73
	s_nop 0
	v_fma_f32 v75, -v73, v74, 1.0
	v_fmac_f32_e32 v74, v75, v74
	v_div_scale_f32 v75, vcc, 1.0, v72, 1.0
	v_mul_f32_e32 v107, v75, v74
	v_fma_f32 v108, -v73, v107, v75
	v_fmac_f32_e32 v107, v108, v74
	v_fma_f32 v73, -v73, v107, v75
	v_div_fmas_f32 v73, v73, v74, v107
	v_div_fixup_f32 v72, v73, v72, 1.0
	v_pk_mul_f32 v[32:33], v[32:33], v[72:73] op_sel_hi:[1,0]
	s_waitcnt vmcnt(1)
	v_lshlrev_b32_e32 v74, 16, v52
	v_and_b32_e32 v75, 0xffff0000, v52
	s_waitcnt vmcnt(0)
	v_pk_mul_f32 v[32:33], v[68:69], v[32:33]
	v_pk_mul_f32 v[34:35], v[34:35], v[72:73] op_sel_hi:[1,0]
	v_pk_mul_f32 v[32:33], v[32:33], v[74:75]
	v_lshlrev_b32_e32 v74, 16, v53
	v_and_b32_e32 v75, 0xffff0000, v53
	v_pk_mul_f32 v[34:35], v[70:71], v[34:35]
	v_pk_mul_f32 v[36:37], v[36:37], v[72:73] op_sel_hi:[1,0]
	v_pk_mul_f32 v[34:35], v[34:35], v[74:75]
	v_cvt_pk_bf16_f32 v32, v32, v33
	v_cvt_pk_bf16_f32 v33, v34, v35
	v_lshlrev_b32_e32 v34, 16, v54
	v_and_b32_e32 v35, 0xffff0000, v54
	v_pk_mul_f32 v[36:37], v[64:65], v[36:37]
	v_pk_mul_f32 v[38:39], v[38:39], v[72:73] op_sel_hi:[1,0]
	v_pk_mul_f32 v[34:35], v[36:37], v[34:35]
	v_lshlrev_b32_e32 v36, 16, v55
	v_and_b32_e32 v37, 0xffff0000, v55
	v_pk_mul_f32 v[38:39], v[66:67], v[38:39]
	v_cvt_pk_bf16_f32 v34, v34, v35
	v_pk_mul_f32 v[36:37], v[38:39], v[36:37]
	v_pk_mul_f32 v[38:39], v[40:41], v[72:73] op_sel_hi:[1,0]
	v_cvt_pk_bf16_f32 v35, v36, v37
	v_lshlrev_b32_e32 v36, 16, v48
	v_and_b32_e32 v37, 0xffff0000, v48
	v_pk_mul_f32 v[38:39], v[60:61], v[38:39]
	v_pk_mul_f32 v[40:41], v[42:43], v[72:73] op_sel_hi:[1,0]
	v_pk_mul_f32 v[36:37], v[38:39], v[36:37]
	v_lshlrev_b32_e32 v38, 16, v49
	v_and_b32_e32 v39, 0xffff0000, v49
	v_pk_mul_f32 v[40:41], v[62:63], v[40:41]
	v_cvt_pk_bf16_f32 v36, v36, v37
	v_pk_mul_f32 v[38:39], v[40:41], v[38:39]
	v_pk_mul_f32 v[40:41], v[44:45], v[72:73] op_sel_hi:[1,0]
	v_cvt_pk_bf16_f32 v37, v38, v39
	v_lshlrev_b32_e32 v38, 16, v50
	v_and_b32_e32 v39, 0xffff0000, v50
	v_pk_mul_f32 v[40:41], v[56:57], v[40:41]
	v_pk_mul_f32 v[42:43], v[46:47], v[72:73] op_sel_hi:[1,0]
	v_pk_mul_f32 v[38:39], v[40:41], v[38:39]
	v_lshlrev_b32_e32 v40, 16, v51
	v_and_b32_e32 v41, 0xffff0000, v51
	v_pk_mul_f32 v[42:43], v[58:59], v[42:43]
	v_cvt_pk_bf16_f32 v38, v38, v39
	v_pk_mul_f32 v[40:41], v[42:43], v[40:41]
	s_nop 0
	v_cvt_pk_bf16_f32 v39, v40, v41
	v_lshl_add_u64 v[40:41], s[42:43], 0, v[78:79]
	v_add_co_u32_e32 v40, vcc, 0x10400000, v40
	s_nop 1
	v_addc_co_u32_e32 v41, vcc, 0, v41, vcc
	s_andn2_b64 vcc, exec, s[68:69]
	global_store_dwordx4 v[40:41], v[32:35], off
	global_store_dwordx4 v[40:41], v[36:39], off offset:16
	s_cbranch_vccnz .LBB0_3036
	v_lshl_add_u64 v[32:33], s[42:43], 0, v[76:77]
	s_mov_b64 s[38:39], 0x5310000
	v_lshl_add_u64 v[34:35], v[32:33], 0, s[38:39]
	v_add_co_u32_e32 v32, vcc, 0x5310000, v32
	s_nop 1
	v_addc_co_u32_e32 v33, vcc, 0, v33, vcc
	global_load_dwordx4 v[52:55], v[32:33], off
	global_load_dwordx4 v[48:51], v[34:35], off offset:16
	s_branch .LBB0_3036
